# in-proj GEMM: column-tile order remapped (pn ^= ((pn>>2)&1)<<5) so every workgroup gets exactly one rotary tile instead of two or none (same tiles, bit-identical)
# baseline (speedup 1.0000x reference)
;     __device__ __forceinline__ bool next(int i, Unit& u) const {
;         const int z = i % nz; const long L = (long)(i / nz) * G + c; if (L >= nwg) return false;
;         int wgid = (int)L; { const int q = nwg / NXCD, r = nwg % NXCD, xcd = wgid % NXCD, off = wgid / NXCD; wgid = (xcd < r ? xcd * (q + 1) : r * (q + 1) + (xcd - r) * q) + off; }
;         const int nig = WGM * nN, gid = wgid / nig, fm = gid * WGM, gsz = (nM - fm) < WGM ? (nM - fm) : WGM;
;         u.pm = fm + ((wgid % nig) % gsz); u.pn = (wgid % nig) / gsz; u.z = z; return true;
;     }
; template <class Epi>
; __device__ __forceinline__ void gemm_phase(LAS unsigned char* lds, const Sched& S, const Epi& E) {
;     ...
;         if (!E.keep(cur))
; #pragma unroll
;         for (int a = 0; a < 2; ++a)
; #pragma unroll
;             for (int b = 0; b < 2; ++b)
; #pragma unroll
;                 for (int m = 0; m < 4; ++m)
; #pragma unroll
;                     for (int n = 0; n < 2; ++n) acc[a][b][m][n] = (f32x4){0.f, 0.f, 0.f, 0.f};
.LBB0_152:
	s_bfe_u32 s8, s52, 0x10002
	s_lshl_b32 s8, s8, 5
	s_xor_b32 s52, s52, s8
	s_ashr_i32 s55, s54, 31
	s_lshl_b64 s[56:57], s[54:55], 20
	s_add_u32 s56, s4, s56
	s_addc_u32 s57, s5, s57
	s_and_b64 s[58:59], s[40:41], exec
	s_cselect_b32 s55, s57, s43
	s_cselect_b32 s73, s56, s42
	s_ashr_i32 s53, s52, 31
	s_lshl_b64 s[58:59], s[52:53], 20
	s_add_u32 s58, s6, s58
	s_addc_u32 s59, s7, s59
	s_and_b64 s[60:61], s[40:41], exec
	s_cselect_b32 s53, s59, s45
	s_cselect_b32 s76, s58, s44
	s_add_u32 s42, s42, 0x80080
	s_addc_u32 s43, s43, 0
	s_add_u32 s77, s44, 0x100
	v_mov_b32_e32 v2, 0
	s_mov_b32 s10, s82
	s_addc_u32 s81, s45, 0
	s_mov_b32 s82, -2
	v_mov_b32_e32 v3, v2
	v_mov_b32_e32 v4, v2
	v_mov_b32_e32 v5, v2
	v_mov_b32_e32 v6, v2
	v_mov_b32_e32 v7, v2
	v_mov_b32_e32 v8, v2
	v_mov_b32_e32 v9, v2
	v_mov_b32_e32 v18, v2
	v_mov_b32_e32 v19, v2
	v_mov_b32_e32 v20, v2
	v_mov_b32_e32 v21, v2
	v_mov_b32_e32 v22, v2
	v_mov_b32_e32 v23, v2
	v_mov_b32_e32 v24, v2
	v_mov_b32_e32 v25, v2
	v_mov_b32_e32 v34, v2
	v_mov_b32_e32 v35, v2
	v_mov_b32_e32 v36, v2
	v_mov_b32_e32 v37, v2
	v_mov_b32_e32 v38, v2
	v_mov_b32_e32 v39, v2
	v_mov_b32_e32 v40, v2
	v_mov_b32_e32 v41, v2
	v_mov_b32_e32 v50, v2
	v_mov_b32_e32 v51, v2
	v_mov_b32_e32 v52, v2
	v_mov_b32_e32 v53, v2
	v_mov_b32_e32 v54, v2
	v_mov_b32_e32 v55, v2
	v_mov_b32_e32 v56, v2
	v_mov_b32_e32 v57, v2
	v_mov_b32_e32 v10, v2
	v_mov_b32_e32 v11, v2
	v_mov_b32_e32 v12, v2
	v_mov_b32_e32 v13, v2
	v_mov_b32_e32 v14, v2
	v_mov_b32_e32 v15, v2
	v_mov_b32_e32 v16, v2
	v_mov_b32_e32 v17, v2
	v_mov_b32_e32 v26, v2
	v_mov_b32_e32 v27, v2
	v_mov_b32_e32 v28, v2
	v_mov_b32_e32 v29, v2
	v_mov_b32_e32 v30, v2
	v_mov_b32_e32 v31, v2
	v_mov_b32_e32 v32, v2
	v_mov_b32_e32 v33, v2
	v_mov_b32_e32 v42, v2
	v_mov_b32_e32 v43, v2
	v_mov_b32_e32 v44, v2
	v_mov_b32_e32 v45, v2
	v_mov_b32_e32 v46, v2
	v_mov_b32_e32 v47, v2
	v_mov_b32_e32 v48, v2
	v_mov_b32_e32 v49, v2
	v_mov_b32_e32 v58, v2
	v_mov_b32_e32 v59, v2
	v_mov_b32_e32 v60, v2
	v_mov_b32_e32 v61, v2
	v_mov_b32_e32 v62, v2
	v_mov_b32_e32 v63, v2
	v_mov_b32_e32 v64, v2
	v_mov_b32_e32 v65, v2
	v_mov_b32_e32 v66, v2
	v_mov_b32_e32 v67, v2
	v_mov_b32_e32 v68, v2
	v_mov_b32_e32 v69, v2
	v_mov_b32_e32 v70, v2
	v_mov_b32_e32 v71, v2
	v_mov_b32_e32 v72, v2
	v_mov_b32_e32 v73, v2
	v_mov_b32_e32 v82, v2
	v_mov_b32_e32 v83, v2
	v_mov_b32_e32 v84, v2
	v_mov_b32_e32 v85, v2
	v_mov_b32_e32 v86, v2
	v_mov_b32_e32 v87, v2
	v_mov_b32_e32 v88, v2
	v_mov_b32_e32 v89, v2
	v_mov_b32_e32 v98, v2
	v_mov_b32_e32 v99, v2
	v_mov_b32_e32 v100, v2
	v_mov_b32_e32 v101, v2
	v_mov_b32_e32 v102, v2
	v_mov_b32_e32 v103, v2
	v_mov_b32_e32 v104, v2
	v_mov_b32_e32 v105, v2
	v_mov_b32_e32 v114, v2
	v_mov_b32_e32 v115, v2
	v_mov_b32_e32 v116, v2
	v_mov_b32_e32 v117, v2
	v_mov_b32_e32 v118, v2
	v_mov_b32_e32 v119, v2
	v_mov_b32_e32 v120, v2
	v_mov_b32_e32 v121, v2
	v_mov_b32_e32 v74, v2
	v_mov_b32_e32 v75, v2
	v_mov_b32_e32 v76, v2
	v_mov_b32_e32 v77, v2
	v_mov_b32_e32 v78, v2
	v_mov_b32_e32 v79, v2
	v_mov_b32_e32 v80, v2
	v_mov_b32_e32 v81, v2
	v_mov_b32_e32 v90, v2
	v_mov_b32_e32 v91, v2
	v_mov_b32_e32 v92, v2
	v_mov_b32_e32 v93, v2
	v_mov_b32_e32 v94, v2
	v_mov_b32_e32 v95, v2
	v_mov_b32_e32 v96, v2
	v_mov_b32_e32 v97, v2
	v_mov_b32_e32 v106, v2
	v_mov_b32_e32 v107, v2
	v_mov_b32_e32 v108, v2
	v_mov_b32_e32 v109, v2
	v_mov_b32_e32 v110, v2
	v_mov_b32_e32 v111, v2
	v_mov_b32_e32 v112, v2
	v_mov_b32_e32 v113, v2
	v_mov_b32_e32 v122, v2
	v_mov_b32_e32 v123, v2
	v_mov_b32_e32 v124, v2
	v_mov_b32_e32 v125, v2
	v_mov_b32_e32 v126, v2
	v_mov_b32_e32 v127, v2
	v_mov_b32_e32 v128, v2
	v_mov_b32_e32 v129, v2
